# NSA: (b,g) groups mapped XCD-local, static prio for waves 4-7, 64 accumulator shadow copies moved out of selected-branch loop, mid-iteration vmcnt(0) removed
# speedup vs baseline: 1.0125x; 1.0125x over previous
.LBB0_649:
	s_or_b64 exec, exec, s[2:3]
	s_waitcnt lgkmcnt(0)
	s_barrier
	s_cmp_ge_u32 s83, 0x100
	s_cbranch_scc0 .Lnsa_prio_done
	s_setprio 1
.Lnsa_prio_done:
	s_mov_b32 s0, s92
	s_branch .LBB0_651

.LBB0_651:
	s_cmpk_gt_i32 s0, 0xff
	s_cbranch_scc1 .LBB0_784
	s_mov_b32 s78, s0
	s_and_b32 s1, s0, 7
	s_lshl_b32 s1, s1, 5
	s_lshr_b32 s0, s0, 3
	s_or_b32 s0, s0, s1
	s_and_b32 s1, s0, 31
	s_xor_b32 s2, s1, 63
	v_writelane_b32 v248, s2, 34
	s_or_b32 s2, s1, 64
	s_bfe_u32 s4, s0, 0x20005
	v_writelane_b32 v248, s2, 35
	s_mov_b32 s93, s1
	s_xor_b32 s1, s1, 0x7f
	s_ashr_i32 s0, s0, 7
	v_writelane_b32 v248, s1, 36
	s_ashr_i32 s1, s0, 31
	s_lshl_b64 s[2:3], s[0:1], 2
	s_or_b32 s2, s2, s4
	s_lshl_b64 s[8:9], s[2:3], 13
	v_writelane_b32 v248, s8, 37
	s_lshl_b32 s5, s4, 2
	s_lshl_b32 s6, s4, 17
	v_writelane_b32 v248, s9, 38
	v_writelane_b32 v248, s5, 39
	s_lshl_b32 s7, s4, 9
	s_lshl_b64 s[4:5], s[2:3], 16
	s_lshl_b64 s[2:3], s[2:3], 20
	v_writelane_b32 v248, s2, 40
	s_lshl_b64 s[54:55], s[0:1], 13
	s_lshl_b64 s[86:87], s[0:1], 19
	v_writelane_b32 v248, s3, 41
	s_lshl_b32 s0, s7, 1
	v_writelane_b32 v248, s0, 42
	v_writelane_b32 v248, s54, 43
	s_lshl_b64 s[56:57], s[4:5], 1
	s_or_b32 s86, s86, s6
	v_writelane_b32 v248, s55, 44
	s_mov_b32 s1, 0
	v_writelane_b32 v248, s56, 45
	s_nop 1
	v_writelane_b32 v248, s57, 46
	s_branch .LBB0_654

.LBB0_670:
	s_or_b64 exec, exec, s[8:9]
	v_mul_f32_e32 v82, v148, v82
	v_mul_f32_e32 v196, v148, v66
	v_mul_f32_e32 v66, v148, v83
	v_mul_f32_e32 v83, v148, v67
	v_mul_f32_e32 v67, v148, v84
	v_mul_f32_e32 v84, v148, v68
	v_mul_f32_e32 v68, v148, v85
	v_mul_f32_e32 v85, v148, v69
	v_mul_f32_e32 v69, v148, v86
	v_mul_f32_e32 v86, v148, v70
	v_mul_f32_e32 v70, v148, v87
	v_mul_f32_e32 v87, v148, v71
	v_mul_f32_e32 v71, v148, v88
	v_mul_f32_e32 v88, v148, v72
	v_mul_f32_e32 v72, v148, v89
	v_mul_f32_e32 v89, v148, v73
	v_mul_f32_e32 v73, v148, v90
	v_mul_f32_e32 v90, v148, v74
	v_mul_f32_e32 v74, v148, v91
	v_mul_f32_e32 v91, v148, v75
	v_mul_f32_e32 v75, v148, v92
	v_mul_f32_e32 v92, v148, v76
	v_mul_f32_e32 v76, v148, v93
	v_mul_f32_e32 v93, v148, v77
	v_mul_f32_e32 v77, v148, v94
	v_mul_f32_e32 v94, v148, v78
	v_mul_f32_e32 v78, v148, v95
	v_mul_f32_e32 v95, v148, v79
	v_mul_f32_e32 v79, v148, v96
	v_mul_f32_e32 v96, v148, v80
	v_mul_f32_e32 v80, v148, v97
	v_mul_f32_e32 v81, v148, v81
	v_cvt_pk_bf16_f32 v66, v82, v66
	v_add_u32_e32 v212, s18, v153
	v_add_u32_e32 v82, s18, v147
	v_cvt_pk_bf16_f32 v67, v67, v68
	v_cvt_pk_bf16_f32 v68, v69, v70
	v_cvt_pk_bf16_f32 v69, v71, v72
	v_cvt_pk_bf16_f32 v70, v73, v74
	v_cvt_pk_bf16_f32 v71, v75, v76
	v_cvt_pk_bf16_f32 v72, v77, v78
	v_cvt_pk_bf16_f32 v73, v79, v80
	v_cvt_pk_bf16_f32 v74, v196, v83
	v_cvt_pk_bf16_f32 v75, v84, v85
	v_cvt_pk_bf16_f32 v76, v86, v87
	v_cvt_pk_bf16_f32 v77, v88, v89
	v_cvt_pk_bf16_f32 v78, v90, v91
	v_cvt_pk_bf16_f32 v79, v92, v93
	v_cvt_pk_bf16_f32 v80, v94, v95
	v_cvt_pk_bf16_f32 v81, v96, v81
	v_add3_u32 v84, v212, v108, v178
	v_add3_u32 v96, v82, v178, v153
	ds_read_b64_tr_b16 v[82:83], v84 offset:32768
	ds_read_b64_tr_b16 v[86:87], v84 offset:36864
	ds_read_b64_tr_b16 v[90:91], v84 offset:40960
	ds_read_b64_tr_b16 v[94:95], v84 offset:45056
	ds_read_b64_tr_b16 v[84:85], v96 offset:34816
	ds_read_b64_tr_b16 v[88:89], v96 offset:38912
	ds_read_b64_tr_b16 v[92:93], v96 offset:43008
	ds_read_b64_tr_b16 v[96:97], v96 offset:47104
	v_add_u32_e32 v196, s18, v155
	s_waitcnt lgkmcnt(9)
	v_add3_u32 v198, v212, v154, v178
	v_add3_u32 v210, v196, v178, v153
	ds_read_b64_tr_b16 v[196:197], v198 offset:32768
	s_waitcnt lgkmcnt(9)
	ds_read_b64_tr_b16 v[200:201], v198 offset:36864
	ds_read_b64_tr_b16 v[204:205], v198 offset:40960
	ds_read_b64_tr_b16 v[208:209], v198 offset:45056
	ds_read_b64_tr_b16 v[198:199], v210 offset:34816
	ds_read_b64_tr_b16 v[202:203], v210 offset:38912
	ds_read_b64_tr_b16 v[206:207], v210 offset:43008
	ds_read_b64_tr_b16 v[210:211], v210 offset:47104
	s_waitcnt lgkmcnt(11)
	v_mfma_f32_32x32x16_bf16 v[50:65], v[66:69], v[82:85], v[50:65]
	s_waitcnt lgkmcnt(10)
	v_mfma_f32_32x32x16_bf16 v[50:65], v[70:73], v[86:89], v[50:65]
	s_waitcnt lgkmcnt(9)
	v_mfma_f32_32x32x16_bf16 v[50:65], v[74:77], v[90:93], v[50:65]
	s_waitcnt lgkmcnt(8)
	v_mfma_f32_32x32x16_bf16 v[50:65], v[78:81], v[94:97], v[50:65]
	v_add_u32_e32 v82, s18, v159
	v_add3_u32 v84, v212, v158, v178
	v_add3_u32 v96, v82, v178, v153
	ds_read_b64_tr_b16 v[82:83], v84 offset:32768
	ds_read_b64_tr_b16 v[86:87], v84 offset:36864
	ds_read_b64_tr_b16 v[90:91], v84 offset:40960
	ds_read_b64_tr_b16 v[94:95], v84 offset:45056
	ds_read_b64_tr_b16 v[84:85], v96 offset:34816
	ds_read_b64_tr_b16 v[88:89], v96 offset:38912
	ds_read_b64_tr_b16 v[92:93], v96 offset:43008
	ds_read_b64_tr_b16 v[96:97], v96 offset:47104
	s_waitcnt lgkmcnt(11)
	v_mfma_f32_32x32x16_bf16 v[34:49], v[66:69], v[196:199], v[34:49]
	s_waitcnt lgkmcnt(10)
	v_mfma_f32_32x32x16_bf16 v[34:49], v[70:73], v[200:203], v[34:49]
	s_waitcnt lgkmcnt(9)
	v_mfma_f32_32x32x16_bf16 v[34:49], v[74:77], v[204:207], v[34:49]
	s_waitcnt lgkmcnt(8)
	v_mfma_f32_32x32x16_bf16 v[34:49], v[78:81], v[208:211], v[34:49]
	v_add_u32_e32 v196, s18, v161
	v_add3_u32 v198, v212, v160, v178
	v_add3_u32 v210, v196, v178, v153
	ds_read_b64_tr_b16 v[196:197], v198 offset:32768
	ds_read_b64_tr_b16 v[200:201], v198 offset:36864
	ds_read_b64_tr_b16 v[204:205], v198 offset:40960
	ds_read_b64_tr_b16 v[208:209], v198 offset:45056
	ds_read_b64_tr_b16 v[198:199], v210 offset:34816
	ds_read_b64_tr_b16 v[202:203], v210 offset:38912
	ds_read_b64_tr_b16 v[206:207], v210 offset:43008
	ds_read_b64_tr_b16 v[210:211], v210 offset:47104
	s_waitcnt lgkmcnt(11)
	v_mfma_f32_32x32x16_bf16 v[18:33], v[66:69], v[82:85], v[18:33]
	s_waitcnt lgkmcnt(10)
	v_mfma_f32_32x32x16_bf16 v[18:33], v[70:73], v[86:89], v[18:33]
	s_waitcnt lgkmcnt(9)
	v_mfma_f32_32x32x16_bf16 v[18:33], v[74:77], v[90:93], v[18:33]
	s_waitcnt lgkmcnt(8)
	v_mfma_f32_32x32x16_bf16 v[18:33], v[78:81], v[94:97], v[18:33]
	s_waitcnt lgkmcnt(3)
	v_mfma_f32_32x32x16_bf16 v[2:17], v[66:69], v[196:199], v[2:17]
	s_waitcnt lgkmcnt(2)
	v_mfma_f32_32x32x16_bf16 v[2:17], v[70:73], v[200:203], v[2:17]
	s_waitcnt lgkmcnt(1)
	v_mfma_f32_32x32x16_bf16 v[2:17], v[74:77], v[204:207], v[2:17]
	s_waitcnt lgkmcnt(0)
	v_mfma_f32_32x32x16_bf16 v[2:17], v[78:81], v[208:211], v[2:17]
	s_waitcnt vmcnt(0) lgkmcnt(0)
	s_barrier
	s_add_i32 s16, s16, 64
	s_add_i32 s17, s17, 1
	s_cmp_lg_u32 s11, s16
	v_lshl_add_u64 v[102:103], v[102:103], 0, s[34:35]
	s_cbranch_scc0 .LBB0_691

.LBB0_675:
	s_add_i32 s18, s18, 0
	v_add_u32_e32 v70, s18, v0
	v_add_u32_e32 v74, s18, v107
	ds_read_b128 v[66:69], v70
	ds_read_b128 v[70:73], v70 offset:8192
	ds_read_b128 v[196:199], v74
	ds_read_b128 v[200:203], v74 offset:8192
	v_add_u32_e32 v74, s18, v109
	ds_read_b128 v[204:207], v74
	ds_read_b128 v[208:211], v74 offset:8192
	s_waitcnt lgkmcnt(0)
	v_mfma_f32_32x32x16_bf16 v[82:97], v[66:69], v[140:143], 0
	v_mfma_f32_32x32x16_bf16 v[66:81], v[70:73], v[140:143], 0
	v_add_u32_e32 v216, s18, v110
	ds_read_b128 v[212:215], v216
	ds_read_b128 v[216:219], v216 offset:8192
	v_mfma_f32_32x32x16_bf16 v[82:97], v[196:199], v[136:139], v[82:97]
	v_mfma_f32_32x32x16_bf16 v[66:81], v[200:203], v[136:139], v[66:81]
	v_add_u32_e32 v200, s18, v111
	ds_read_b128 v[196:199], v200
	ds_read_b128 v[200:203], v200 offset:8192
	v_mfma_f32_32x32x16_bf16 v[82:97], v[204:207], v[132:135], v[82:97]
	v_mfma_f32_32x32x16_bf16 v[66:81], v[208:211], v[132:135], v[66:81]
	v_add_u32_e32 v208, s18, v144
	ds_read_b128 v[204:207], v208
	ds_read_b128 v[208:211], v208 offset:8192
	s_waitcnt lgkmcnt(0)
	v_mfma_f32_32x32x16_bf16 v[82:97], v[212:215], v[128:131], v[82:97]
	v_mfma_f32_32x32x16_bf16 v[66:81], v[216:219], v[128:131], v[66:81]
	v_add_u32_e32 v216, s18, v145
	ds_read_b128 v[212:215], v216
	ds_read_b128 v[216:219], v216 offset:8192
	v_mfma_f32_32x32x16_bf16 v[82:97], v[196:199], v[124:127], v[82:97]
	v_mfma_f32_32x32x16_bf16 v[66:81], v[200:203], v[124:127], v[66:81]
	v_add_u32_e32 v200, s18, v146
	ds_read_b128 v[196:199], v200
	ds_read_b128 v[200:203], v200 offset:8192
	v_mfma_f32_32x32x16_bf16 v[82:97], v[204:207], v[120:123], v[82:97]
	v_mfma_f32_32x32x16_bf16 v[66:81], v[208:211], v[120:123], v[66:81]
	s_waitcnt lgkmcnt(0)
	v_mfma_f32_32x32x16_bf16 v[82:97], v[212:215], v[116:119], v[82:97]
	v_mfma_f32_32x32x16_bf16 v[66:81], v[216:219], v[116:119], v[66:81]
	v_mfma_f32_32x32x16_bf16 v[82:97], v[196:199], v[112:115], v[82:97]
	v_mfma_f32_32x32x16_bf16 v[66:81], v[200:203], v[112:115], v[66:81]
	s_nop 10
	v_exp_f32_e32 v82, v82
	v_exp_f32_e32 v83, v83
	v_exp_f32_e32 v84, v84
	v_add_u32_e32 v196, s16, v187
	v_exp_f32_e32 v85, v85
	v_mul_f32_e32 v82, v106, v82
	v_cmp_le_i32_e32 vcc, v196, v100
	v_mul_f32_e32 v83, v106, v83
	v_add_u32_e32 v197, 2, v196
	v_cndmask_b32_e32 v82, 0, v82, vcc
	v_cmp_lt_i32_e32 vcc, v196, v100
	v_mul_f32_e32 v84, v106, v84
	v_mul_f32_e32 v85, v106, v85
	v_cndmask_b32_e32 v83, 0, v83, vcc
	v_cmp_le_i32_e32 vcc, v197, v100
	v_add_u32_e32 v197, 3, v196
	s_nop 0
	v_cndmask_b32_e32 v84, 0, v84, vcc
	v_cmp_le_i32_e32 vcc, v197, v100
	v_add_f32_e32 v197, v82, v83
	s_nop 0
	v_cndmask_b32_e32 v85, 0, v85, vcc
	v_add_f32_e32 v198, v84, v85
	v_add_f32_e32 v197, v197, v198
	v_mbcnt_lo_u32_b32 v198, -1, 0
	v_mbcnt_hi_u32_b32 v198, -1, v198
	v_mbcnt_lo_u32_b32 v199, -1, 0
	v_mbcnt_hi_u32_b32 v199, -1, v199
	v_mbcnt_lo_u32_b32 v200, -1, 0
	v_mbcnt_hi_u32_b32 v200, -1, v200
	s_nop 0
	v_lshlrev_b32_e32 v198, 2, v198
	v_xor_b32_e32 v198, 4, v198
	ds_bpermute_b32 v198, v198, v197
	v_lshlrev_b32_e32 v200, 2, v200
	v_xor_b32_e32 v200, 4, v200
	ds_bpermute_b32 v200, v200, v85
	s_waitcnt lgkmcnt(0)
	v_add_f32_e32 v198, v197, v198
	v_lshlrev_b32_e32 v197, 2, v199
	v_xor_b32_e32 v197, 8, v197
	ds_bpermute_b32 v199, v197, v198
	v_mbcnt_lo_u32_b32 v197, -1, 0
	v_mbcnt_hi_u32_b32 v197, -1, v197
	v_add_f32_e32 v200, v85, v200
	v_lshlrev_b32_e32 v197, 2, v197
	v_xor_b32_e32 v197, 8, v197
	ds_bpermute_b32 v201, v197, v200
	v_add_u32_e32 v197, s16, v195
	s_and_saveexec_b64 s[8:9], s[4:5]
	s_cbranch_execz .LBB0_677
	v_add_u32_e32 v202, 0x10000, v197
	s_waitcnt lgkmcnt(0)
	v_add_f32_e32 v198, v198, v199
	v_add_u32_e32 v203, 0x10004, v197
	v_add_f32_e32 v199, v200, v201
	ds_add_f32 v202, v198
	ds_add_f32 v203, v199
.LBB0_677:
	s_or_b64 exec, exec, s[8:9]
	v_exp_f32_e32 v86, v86
	v_exp_f32_e32 v87, v87
	v_exp_f32_e32 v88, v88
	v_add_u32_e32 v198, 8, v196
	v_exp_f32_e32 v89, v89
	v_mul_f32_e32 v86, v106, v86
	v_cmp_le_i32_e32 vcc, v198, v100
	v_add_u32_e32 v198, 9, v196
	v_mul_f32_e32 v87, v106, v87
	v_cndmask_b32_e32 v86, 0, v86, vcc
	v_cmp_le_i32_e32 vcc, v198, v100
	v_add_u32_e32 v198, 10, v196
	v_mul_f32_e32 v88, v106, v88
	v_cndmask_b32_e32 v87, 0, v87, vcc
	v_cmp_le_i32_e32 vcc, v198, v100
	v_add_u32_e32 v198, 11, v196
	v_mul_f32_e32 v89, v106, v89
	v_cndmask_b32_e32 v88, 0, v88, vcc
	v_cmp_le_i32_e32 vcc, v198, v100
	v_add_f32_e32 v198, v86, v87
	s_nop 0
	v_cndmask_b32_e32 v89, 0, v89, vcc
	s_waitcnt lgkmcnt(0)
	v_add_f32_e32 v199, v88, v89
	v_add_f32_e32 v198, v198, v199
	v_mbcnt_lo_u32_b32 v199, -1, 0
	v_mbcnt_hi_u32_b32 v199, -1, v199
	v_mbcnt_lo_u32_b32 v200, -1, 0
	v_mbcnt_hi_u32_b32 v200, -1, v200
	v_mbcnt_lo_u32_b32 v201, -1, 0
	v_mbcnt_hi_u32_b32 v201, -1, v201
	s_nop 0
	v_lshlrev_b32_e32 v199, 2, v199
	v_lshlrev_b32_e32 v201, 2, v201
	v_xor_b32_e32 v199, 4, v199
	v_xor_b32_e32 v201, 4, v201
	ds_bpermute_b32 v199, v199, v198
	ds_bpermute_b32 v201, v201, v89
	s_waitcnt lgkmcnt(0)
	v_add_f32_e32 v198, v198, v199
	v_lshlrev_b32_e32 v199, 2, v200
	v_add_f32_e32 v200, v89, v201
	v_mbcnt_lo_u32_b32 v201, -1, 0
	v_mbcnt_hi_u32_b32 v201, -1, v201
	v_xor_b32_e32 v199, 8, v199
	v_lshlrev_b32_e32 v201, 2, v201
	v_xor_b32_e32 v201, 8, v201
	ds_bpermute_b32 v199, v199, v198
	ds_bpermute_b32 v201, v201, v200
	s_and_saveexec_b64 s[8:9], s[4:5]
	s_cbranch_execz .LBB0_679
	v_add_u32_e32 v202, 0x10008, v197
	s_waitcnt lgkmcnt(0)
	v_add_f32_e32 v198, v198, v199
	v_add_u32_e32 v203, 0x1000c, v197
	v_add_f32_e32 v199, v200, v201
	ds_add_f32 v202, v198
	ds_add_f32 v203, v199
.LBB0_679:
	s_or_b64 exec, exec, s[8:9]
	v_exp_f32_e32 v90, v90
	v_exp_f32_e32 v91, v91
	v_exp_f32_e32 v92, v92
	v_add_u32_e32 v198, 16, v196
	v_exp_f32_e32 v93, v93
	v_mul_f32_e32 v90, v106, v90
	v_cmp_le_i32_e32 vcc, v198, v100
	v_add_u32_e32 v198, 17, v196
	v_mul_f32_e32 v91, v106, v91
	v_cndmask_b32_e32 v90, 0, v90, vcc
	v_cmp_le_i32_e32 vcc, v198, v100
	v_add_u32_e32 v198, 18, v196
	v_mul_f32_e32 v92, v106, v92
	v_cndmask_b32_e32 v91, 0, v91, vcc
	v_cmp_le_i32_e32 vcc, v198, v100
	v_add_u32_e32 v198, 19, v196
	v_mul_f32_e32 v93, v106, v93
	v_cndmask_b32_e32 v92, 0, v92, vcc
	v_cmp_le_i32_e32 vcc, v198, v100
	v_add_f32_e32 v198, v90, v91
	s_nop 0
	v_cndmask_b32_e32 v93, 0, v93, vcc
	s_waitcnt lgkmcnt(0)
	v_add_f32_e32 v199, v92, v93
	v_add_f32_e32 v198, v198, v199
	v_mbcnt_lo_u32_b32 v199, -1, 0
	v_mbcnt_hi_u32_b32 v199, -1, v199
	v_mbcnt_lo_u32_b32 v200, -1, 0
	v_mbcnt_hi_u32_b32 v200, -1, v200
	v_mbcnt_lo_u32_b32 v201, -1, 0
	v_mbcnt_hi_u32_b32 v201, -1, v201
	s_nop 0
	v_lshlrev_b32_e32 v199, 2, v199
	v_lshlrev_b32_e32 v201, 2, v201
	v_xor_b32_e32 v199, 4, v199
	v_xor_b32_e32 v201, 4, v201
	ds_bpermute_b32 v199, v199, v198
	ds_bpermute_b32 v201, v201, v93
	s_waitcnt lgkmcnt(0)
	v_add_f32_e32 v198, v198, v199
	v_lshlrev_b32_e32 v199, 2, v200
	v_add_f32_e32 v200, v93, v201
	v_mbcnt_lo_u32_b32 v201, -1, 0
	v_mbcnt_hi_u32_b32 v201, -1, v201
	v_xor_b32_e32 v199, 8, v199
	v_lshlrev_b32_e32 v201, 2, v201
	v_xor_b32_e32 v201, 8, v201
	ds_bpermute_b32 v199, v199, v198
	ds_bpermute_b32 v201, v201, v200
	s_and_saveexec_b64 s[8:9], s[4:5]
	s_cbranch_execz .LBB0_681
	v_add_u32_e32 v202, 0x10010, v197
	s_waitcnt lgkmcnt(0)
	v_add_f32_e32 v198, v198, v199
	v_add_u32_e32 v203, 0x10014, v197
	v_add_f32_e32 v199, v200, v201
	ds_add_f32 v202, v198
	ds_add_f32 v203, v199
.LBB0_681:
	s_or_b64 exec, exec, s[8:9]
	v_exp_f32_e32 v94, v94
	v_exp_f32_e32 v95, v95
	v_exp_f32_e32 v96, v96
	v_add_u32_e32 v198, 24, v196
	v_exp_f32_e32 v97, v97
	v_mul_f32_e32 v94, v106, v94
	v_cmp_le_i32_e32 vcc, v198, v100
	v_add_u32_e32 v198, 25, v196
	v_mul_f32_e32 v95, v106, v95
	v_cndmask_b32_e32 v94, 0, v94, vcc
	v_cmp_le_i32_e32 vcc, v198, v100
	v_add_u32_e32 v198, 26, v196
	v_mul_f32_e32 v96, v106, v96
	v_cndmask_b32_e32 v95, 0, v95, vcc
	v_cmp_le_i32_e32 vcc, v198, v100
	v_add_u32_e32 v198, 27, v196
	v_mul_f32_e32 v97, v106, v97
	v_cndmask_b32_e32 v96, 0, v96, vcc
	v_cmp_le_i32_e32 vcc, v198, v100
	v_add_f32_e32 v198, v94, v95
	s_nop 0
	v_cndmask_b32_e32 v97, 0, v97, vcc
	s_waitcnt lgkmcnt(0)
	v_add_f32_e32 v199, v96, v97
	v_add_f32_e32 v198, v198, v199
	v_mbcnt_lo_u32_b32 v199, -1, 0
	v_mbcnt_hi_u32_b32 v199, -1, v199
	v_mbcnt_lo_u32_b32 v200, -1, 0
	v_mbcnt_hi_u32_b32 v200, -1, v200
	v_mbcnt_lo_u32_b32 v201, -1, 0
	v_mbcnt_hi_u32_b32 v201, -1, v201
	s_nop 0
	v_lshlrev_b32_e32 v199, 2, v199
	v_lshlrev_b32_e32 v201, 2, v201
	v_xor_b32_e32 v199, 4, v199
	v_xor_b32_e32 v201, 4, v201
	ds_bpermute_b32 v199, v199, v198
	ds_bpermute_b32 v201, v201, v97
	s_waitcnt lgkmcnt(0)
	v_add_f32_e32 v198, v198, v199
	v_lshlrev_b32_e32 v199, 2, v200
	v_add_f32_e32 v200, v97, v201
	v_mbcnt_lo_u32_b32 v201, -1, 0
	v_mbcnt_hi_u32_b32 v201, -1, v201
	v_xor_b32_e32 v199, 8, v199
	v_lshlrev_b32_e32 v201, 2, v201
	v_xor_b32_e32 v201, 8, v201
	ds_bpermute_b32 v199, v199, v198
	ds_bpermute_b32 v201, v201, v200
	s_and_saveexec_b64 s[8:9], s[4:5]
	s_cbranch_execz .LBB0_683
	v_add_u32_e32 v202, 0x10018, v197
	s_waitcnt lgkmcnt(0)
	v_add_f32_e32 v198, v198, v199
	v_add_u32_e32 v203, 0x1001c, v197
	v_add_f32_e32 v199, v200, v201
	ds_add_f32 v202, v198
	ds_add_f32 v203, v199
.LBB0_683:
	s_or_b64 exec, exec, s[8:9]
	v_exp_f32_e32 v66, v66
	v_exp_f32_e32 v67, v67
	v_exp_f32_e32 v68, v68
	v_add_u32_e32 v198, 32, v196
	v_exp_f32_e32 v69, v69
	v_mul_f32_e32 v66, v106, v66
	v_cmp_le_i32_e32 vcc, v198, v100
	v_add_u32_e32 v198, 33, v196
	v_mul_f32_e32 v67, v106, v67
	v_cndmask_b32_e32 v66, 0, v66, vcc
	v_cmp_le_i32_e32 vcc, v198, v100
	v_add_u32_e32 v198, 34, v196
	v_mul_f32_e32 v68, v106, v68
	v_cndmask_b32_e32 v67, 0, v67, vcc
	v_cmp_le_i32_e32 vcc, v198, v100
	v_add_u32_e32 v198, 35, v196
	v_mul_f32_e32 v69, v106, v69
	v_cndmask_b32_e32 v68, 0, v68, vcc
	v_cmp_le_i32_e32 vcc, v198, v100
	v_add_f32_e32 v198, v66, v67
	s_nop 0
	v_cndmask_b32_e32 v69, 0, v69, vcc
	s_waitcnt lgkmcnt(0)
	v_add_f32_e32 v199, v68, v69
	v_add_f32_e32 v198, v198, v199
	v_mbcnt_lo_u32_b32 v199, -1, 0
	v_mbcnt_hi_u32_b32 v199, -1, v199
	v_mbcnt_lo_u32_b32 v200, -1, 0
	v_mbcnt_hi_u32_b32 v200, -1, v200
	v_mbcnt_lo_u32_b32 v201, -1, 0
	v_mbcnt_hi_u32_b32 v201, -1, v201
	s_nop 0
	v_lshlrev_b32_e32 v199, 2, v199
	v_lshlrev_b32_e32 v201, 2, v201
	v_xor_b32_e32 v199, 4, v199
	v_xor_b32_e32 v201, 4, v201
	ds_bpermute_b32 v199, v199, v198
	ds_bpermute_b32 v201, v201, v69
	s_waitcnt lgkmcnt(0)
	v_add_f32_e32 v198, v198, v199
	v_lshlrev_b32_e32 v199, 2, v200
	v_add_f32_e32 v200, v69, v201
	v_mbcnt_lo_u32_b32 v201, -1, 0
	v_mbcnt_hi_u32_b32 v201, -1, v201
	v_xor_b32_e32 v199, 8, v199
	v_lshlrev_b32_e32 v201, 2, v201
	v_xor_b32_e32 v201, 8, v201
	ds_bpermute_b32 v199, v199, v198
	ds_bpermute_b32 v201, v201, v200
	s_and_saveexec_b64 s[8:9], s[4:5]
	s_cbranch_execz .LBB0_685
	v_add_u32_e32 v202, 0x10020, v197
	s_waitcnt lgkmcnt(0)
	v_add_f32_e32 v198, v198, v199
	v_add_u32_e32 v203, 0x10024, v197
	v_add_f32_e32 v199, v200, v201
	ds_add_f32 v202, v198
	ds_add_f32 v203, v199
.LBB0_685:
	s_or_b64 exec, exec, s[8:9]
	v_exp_f32_e32 v70, v70
	v_exp_f32_e32 v71, v71
	v_exp_f32_e32 v72, v72
	v_add_u32_e32 v198, 40, v196
	v_exp_f32_e32 v73, v73
	v_mul_f32_e32 v70, v106, v70
	v_cmp_le_i32_e32 vcc, v198, v100
	v_add_u32_e32 v198, 41, v196
	v_mul_f32_e32 v71, v106, v71
	v_cndmask_b32_e32 v70, 0, v70, vcc
	v_cmp_le_i32_e32 vcc, v198, v100
	v_add_u32_e32 v198, 42, v196
	v_mul_f32_e32 v72, v106, v72
	v_cndmask_b32_e32 v71, 0, v71, vcc
	v_cmp_le_i32_e32 vcc, v198, v100
	v_add_u32_e32 v198, 43, v196
	v_mul_f32_e32 v73, v106, v73
	v_cndmask_b32_e32 v72, 0, v72, vcc
	v_cmp_le_i32_e32 vcc, v198, v100
	v_add_f32_e32 v198, v70, v71
	s_nop 0
	v_cndmask_b32_e32 v73, 0, v73, vcc
	s_waitcnt lgkmcnt(0)
	v_add_f32_e32 v199, v72, v73
	v_add_f32_e32 v198, v198, v199
	v_mbcnt_lo_u32_b32 v199, -1, 0
	v_mbcnt_hi_u32_b32 v199, -1, v199
	v_mbcnt_lo_u32_b32 v200, -1, 0
	v_mbcnt_hi_u32_b32 v200, -1, v200
	v_mbcnt_lo_u32_b32 v201, -1, 0
	v_mbcnt_hi_u32_b32 v201, -1, v201
	s_nop 0
	v_lshlrev_b32_e32 v199, 2, v199
	v_lshlrev_b32_e32 v201, 2, v201
	v_xor_b32_e32 v199, 4, v199
	v_xor_b32_e32 v201, 4, v201
	ds_bpermute_b32 v199, v199, v198
	ds_bpermute_b32 v201, v201, v73
	s_waitcnt lgkmcnt(0)
	v_add_f32_e32 v198, v198, v199
	v_lshlrev_b32_e32 v199, 2, v200
	v_add_f32_e32 v200, v73, v201
	v_mbcnt_lo_u32_b32 v201, -1, 0
	v_mbcnt_hi_u32_b32 v201, -1, v201
	v_xor_b32_e32 v199, 8, v199
	v_lshlrev_b32_e32 v201, 2, v201
	v_xor_b32_e32 v201, 8, v201
	ds_bpermute_b32 v199, v199, v198
	ds_bpermute_b32 v201, v201, v200
	s_and_saveexec_b64 s[8:9], s[4:5]
	s_cbranch_execz .LBB0_687
	v_add_u32_e32 v202, 0x10028, v197
	s_waitcnt lgkmcnt(0)
	v_add_f32_e32 v198, v198, v199
	v_add_u32_e32 v203, 0x1002c, v197
	v_add_f32_e32 v199, v200, v201
	ds_add_f32 v202, v198
	ds_add_f32 v203, v199
.LBB0_687:
	s_or_b64 exec, exec, s[8:9]
	v_exp_f32_e32 v74, v74
	v_exp_f32_e32 v75, v75
	v_exp_f32_e32 v76, v76
	v_add_u32_e32 v198, 48, v196
	v_exp_f32_e32 v77, v77
	v_mul_f32_e32 v74, v106, v74
	v_cmp_le_i32_e32 vcc, v198, v100
	v_add_u32_e32 v198, 49, v196
	v_mul_f32_e32 v75, v106, v75
	v_cndmask_b32_e32 v74, 0, v74, vcc
	v_cmp_le_i32_e32 vcc, v198, v100
	v_add_u32_e32 v198, 50, v196
	v_mul_f32_e32 v76, v106, v76
	v_cndmask_b32_e32 v75, 0, v75, vcc
	v_cmp_le_i32_e32 vcc, v198, v100
	v_add_u32_e32 v198, 51, v196
	v_mul_f32_e32 v77, v106, v77
	v_cndmask_b32_e32 v76, 0, v76, vcc
	v_cmp_le_i32_e32 vcc, v198, v100
	v_add_f32_e32 v198, v74, v75
	s_nop 0
	v_cndmask_b32_e32 v77, 0, v77, vcc
	s_waitcnt lgkmcnt(0)
	v_add_f32_e32 v199, v76, v77
	v_add_f32_e32 v198, v198, v199
	v_mbcnt_lo_u32_b32 v199, -1, 0
	v_mbcnt_hi_u32_b32 v199, -1, v199
	v_mbcnt_lo_u32_b32 v200, -1, 0
	v_mbcnt_hi_u32_b32 v200, -1, v200
	v_mbcnt_lo_u32_b32 v201, -1, 0
	v_mbcnt_hi_u32_b32 v201, -1, v201
	s_nop 0
	v_lshlrev_b32_e32 v199, 2, v199
	v_lshlrev_b32_e32 v201, 2, v201
	v_xor_b32_e32 v199, 4, v199
	v_xor_b32_e32 v201, 4, v201
	ds_bpermute_b32 v199, v199, v198
	ds_bpermute_b32 v201, v201, v77
	s_waitcnt lgkmcnt(0)
	v_add_f32_e32 v198, v198, v199
	v_lshlrev_b32_e32 v199, 2, v200
	v_add_f32_e32 v200, v77, v201
	v_mbcnt_lo_u32_b32 v201, -1, 0
	v_mbcnt_hi_u32_b32 v201, -1, v201
	v_xor_b32_e32 v199, 8, v199
	v_lshlrev_b32_e32 v201, 2, v201
	v_xor_b32_e32 v201, 8, v201
	ds_bpermute_b32 v199, v199, v198
	ds_bpermute_b32 v201, v201, v200
	s_and_saveexec_b64 s[8:9], s[4:5]
	s_cbranch_execz .LBB0_689
	v_add_u32_e32 v202, 0x10030, v197
	s_waitcnt lgkmcnt(0)
	v_add_f32_e32 v198, v198, v199
	v_add_u32_e32 v203, 0x10034, v197
	v_add_f32_e32 v199, v200, v201
	ds_add_f32 v202, v198
	ds_add_f32 v203, v199
.LBB0_689:
	s_or_b64 exec, exec, s[8:9]
	v_exp_f32_e32 v78, v78
	v_exp_f32_e32 v79, v79
	v_exp_f32_e32 v80, v80
	v_add_u32_e32 v198, 56, v196
	v_exp_f32_e32 v81, v81
	v_mul_f32_e32 v78, v106, v78
	v_cmp_le_i32_e32 vcc, v198, v100
	v_add_u32_e32 v198, 57, v196
	v_mul_f32_e32 v79, v106, v79
	v_cndmask_b32_e32 v78, 0, v78, vcc
	v_cmp_le_i32_e32 vcc, v198, v100
	v_add_u32_e32 v198, 58, v196
	v_mul_f32_e32 v80, v106, v80
	v_cndmask_b32_e32 v79, 0, v79, vcc
	v_cmp_le_i32_e32 vcc, v198, v100
	v_add_u32_e32 v196, 59, v196
	v_mul_f32_e32 v81, v106, v81
	v_cndmask_b32_e32 v80, 0, v80, vcc
	v_cmp_le_i32_e32 vcc, v196, v100
	v_add_f32_e32 v196, v78, v79
	s_nop 0
	v_cndmask_b32_e32 v81, 0, v81, vcc
	v_add_f32_e32 v198, v80, v81
	v_add_f32_e32 v196, v196, v198
	v_mbcnt_lo_u32_b32 v198, -1, 0
	v_mbcnt_hi_u32_b32 v198, -1, v198
	s_waitcnt lgkmcnt(0)
	v_mbcnt_lo_u32_b32 v199, -1, 0
	v_mbcnt_hi_u32_b32 v199, -1, v199
	v_mbcnt_lo_u32_b32 v200, -1, 0
	v_mbcnt_hi_u32_b32 v200, -1, v200
	v_lshlrev_b32_e32 v198, 2, v198
	v_lshlrev_b32_e32 v200, 2, v200
	v_xor_b32_e32 v198, 4, v198
	v_xor_b32_e32 v200, 4, v200
	ds_bpermute_b32 v198, v198, v196
	ds_bpermute_b32 v200, v200, v81
	s_waitcnt lgkmcnt(0)
	v_add_f32_e32 v196, v196, v198
	v_lshlrev_b32_e32 v198, 2, v199
	v_add_f32_e32 v199, v81, v200
	v_mbcnt_lo_u32_b32 v200, -1, 0
	v_mbcnt_hi_u32_b32 v200, -1, v200
	v_xor_b32_e32 v198, 8, v198
	v_lshlrev_b32_e32 v200, 2, v200
	v_xor_b32_e32 v200, 8, v200
	ds_bpermute_b32 v198, v198, v196
	ds_bpermute_b32 v200, v200, v199
	s_and_saveexec_b64 s[8:9], s[4:5]
	s_cbranch_execz .LBB0_670
	v_add_u32_e32 v201, 0x10038, v197
	s_waitcnt lgkmcnt(0)
	v_add_f32_e32 v196, v196, v198
	v_add_u32_e32 v197, 0x1003c, v197
	v_add_f32_e32 v198, v199, v200
	ds_add_f32 v201, v196
	ds_add_f32 v197, v198
	s_branch .LBB0_670

.LBB0_742:
	v_add_f32_e32 v12, v6, v0
	v_add_f32_e32 v12, 0, v12
	v_add_f32_e32 v98, v9, v3
	v_add_f32_e32 v12, v98, v12
	v_add_f32_e32 v98, v8, v2
	v_add_f32_e32 v12, v98, v12
	v_add_f32_e32 v98, v11, v5
	v_add_f32_e32 v12, v98, v12
	v_add_f32_e32 v98, v10, v4
	v_add_f32_e32 v12, v98, v12
	v_add_f32_e32 v98, v13, v7
	v_add_f32_e32 v12, v98, v12
	v_pk_add_f32 v[106:107], v[96:97], v[82:83]
	v_pk_add_f32 v[104:105], v[88:89], v[14:15]
	v_add_f32_e32 v12, v106, v12
	v_add_f32_e32 v12, v107, v12
	v_add_f32_e32 v12, v104, v12
	v_pk_add_f32 v[102:103], v[90:91], v[80:81]
	v_add_f32_e32 v12, v105, v12
	v_add_f32_e32 v12, v102, v12
	v_pk_add_f32 v[100:101], v[92:93], v[84:85]
	v_add_f32_e32 v12, v103, v12
	v_add_f32_e32 v12, v100, v12
	v_pk_add_f32 v[98:99], v[94:95], v[86:87]
	v_add_f32_e32 v12, v101, v12
	v_add_f32_e32 v12, v98, v12
	v_add_f32_e32 v12, v99, v12
	v_cndmask_b32_e64 v12, 0, v12, s[72:73]
	v_cvt_pk_bf16_f32 v6, v6, v9
	v_add_f32_e32 v198, v198, v12
	v_cvt_pk_bf16_f32 v9, v8, v11
	v_cvt_pk_bf16_f32 v10, v10, v13
	v_cvt_pk_bf16_f32 v11, v96, v97
	v_cndmask_b32_e64 v8, 0, v6, s[72:73]
	v_cvt_pk_bf16_f32 v6, v88, v89
	v_cvt_pk_bf16_f32 v12, v90, v91
	v_cvt_pk_bf16_f32 v13, v92, v93
	v_cvt_pk_bf16_f32 v91, v94, v95
	v_cvt_pk_bf16_f32 v0, v0, v3
	v_add_u32_e32 v207, s91, v153
	v_cndmask_b32_e64 v89, 0, v12, s[72:73]
	v_add_u32_e32 v12, s91, v200
	v_cvt_pk_bf16_f32 v3, v2, v5
	v_cvt_pk_bf16_f32 v4, v4, v7
	v_cvt_pk_bf16_f32 v5, v82, v83
	v_cndmask_b32_e64 v2, 0, v0, s[72:73]
	v_cvt_pk_bf16_f32 v0, v14, v15
	v_add3_u32 v14, v207, v199, v178
	v_add3_u32 v94, v12, v178, v153
	v_cndmask_b32_e64 v88, 0, v6, s[72:73]
	v_cndmask_b32_e64 v90, 0, v13, s[72:73]
	v_cvt_pk_bf16_f32 v6, v80, v81
	v_cvt_pk_bf16_f32 v7, v84, v85
	v_cvt_pk_bf16_f32 v99, v86, v87
	ds_read_b64_tr_b16 v[12:13], v14 offset:32768
	ds_read_b64_tr_b16 v[80:81], v14 offset:36864
	ds_read_b64_tr_b16 v[84:85], v14 offset:40960
	ds_read_b64_tr_b16 v[92:93], v14 offset:45056
	ds_read_b64_tr_b16 v[14:15], v94 offset:34816
	ds_read_b64_tr_b16 v[82:83], v94 offset:38912
	ds_read_b64_tr_b16 v[86:87], v94 offset:43008
	ds_read_b64_tr_b16 v[94:95], v94 offset:47104
	v_cndmask_b32_e64 v9, 0, v9, s[72:73]
	v_cndmask_b32_e64 v10, 0, v10, s[72:73]
	v_cndmask_b32_e64 v11, 0, v11, s[72:73]
	v_cndmask_b32_e64 v91, 0, v91, s[72:73]
	v_cndmask_b32_e64 v3, 0, v3, s[72:73]
	v_cndmask_b32_e64 v4, 0, v4, s[72:73]
	v_cndmask_b32_e64 v5, 0, v5, s[72:73]
	v_cndmask_b32_e64 v96, 0, v0, s[72:73]
	v_cndmask_b32_e64 v97, 0, v6, s[72:73]
	v_cndmask_b32_e64 v98, 0, v7, s[72:73]
	v_cndmask_b32_e64 v99, 0, v99, s[72:73]
	v_add3_u32 v0, v207, v201, v178
	v_add_u32_e32 v6, s91, v202
	v_add3_u32 v6, v6, v178, v153
	ds_read_b64_tr_b16 v[100:101], v0 offset:32768
	ds_read_b64_tr_b16 v[104:105], v0 offset:36864
	ds_read_b64_tr_b16 v[108:109], v0 offset:40960
	ds_read_b64_tr_b16 v[208:209], v0 offset:45056
	ds_read_b64_tr_b16 v[102:103], v6 offset:34816
	ds_read_b64_tr_b16 v[106:107], v6 offset:38912
	ds_read_b64_tr_b16 v[110:111], v6 offset:43008
	ds_read_b64_tr_b16 v[210:211], v6 offset:47104
	s_waitcnt lgkmcnt(11)
	v_mfma_f32_32x32x16_bf16 v[64:79], v[8:11], v[12:15], v[64:79]
	s_waitcnt lgkmcnt(10)
	v_mfma_f32_32x32x16_bf16 v[64:79], v[88:91], v[80:83], v[64:79]
	s_waitcnt lgkmcnt(9)
	v_mfma_f32_32x32x16_bf16 v[64:79], v[2:5], v[84:87], v[64:79]
	s_waitcnt lgkmcnt(8)
	v_mfma_f32_32x32x16_bf16 v[64:79], v[96:99], v[92:95], v[64:79]
	v_add3_u32 v0, v207, v203, v178
	v_add_u32_e32 v6, s91, v204
	v_add3_u32 v6, v6, v178, v153
	ds_read_b64_tr_b16 v[12:13], v0 offset:32768
	ds_read_b64_tr_b16 v[80:81], v0 offset:36864
	ds_read_b64_tr_b16 v[84:85], v0 offset:40960
	ds_read_b64_tr_b16 v[92:93], v0 offset:45056
	ds_read_b64_tr_b16 v[14:15], v6 offset:34816
	ds_read_b64_tr_b16 v[82:83], v6 offset:38912
	ds_read_b64_tr_b16 v[86:87], v6 offset:43008
	ds_read_b64_tr_b16 v[94:95], v6 offset:47104
	s_waitcnt lgkmcnt(11)
	v_mfma_f32_32x32x16_bf16 v[48:63], v[8:11], v[100:103], v[48:63]
	s_waitcnt lgkmcnt(10)
	v_mfma_f32_32x32x16_bf16 v[48:63], v[88:91], v[104:107], v[48:63]
	s_waitcnt lgkmcnt(9)
	v_mfma_f32_32x32x16_bf16 v[48:63], v[2:5], v[108:111], v[48:63]
	s_waitcnt lgkmcnt(8)
	v_mfma_f32_32x32x16_bf16 v[48:63], v[96:99], v[208:211], v[48:63]
	v_add3_u32 v0, v207, v205, v178
	v_add_u32_e32 v6, s91, v206
	v_add3_u32 v6, v6, v178, v153
	ds_read_b64_tr_b16 v[100:101], v0 offset:32768
	ds_read_b64_tr_b16 v[104:105], v0 offset:36864
	ds_read_b64_tr_b16 v[108:109], v0 offset:40960
	ds_read_b64_tr_b16 v[208:209], v0 offset:45056
	ds_read_b64_tr_b16 v[102:103], v6 offset:34816
	ds_read_b64_tr_b16 v[106:107], v6 offset:38912
	ds_read_b64_tr_b16 v[110:111], v6 offset:43008
	ds_read_b64_tr_b16 v[210:211], v6 offset:47104
	s_waitcnt lgkmcnt(11)
	v_mfma_f32_32x32x16_bf16 v[32:47], v[8:11], v[12:15], v[32:47]
	s_waitcnt lgkmcnt(10)
	v_mfma_f32_32x32x16_bf16 v[32:47], v[88:91], v[80:83], v[32:47]
	s_waitcnt lgkmcnt(9)
	v_mfma_f32_32x32x16_bf16 v[32:47], v[2:5], v[84:87], v[32:47]
	s_waitcnt lgkmcnt(8)
	v_mfma_f32_32x32x16_bf16 v[32:47], v[96:99], v[92:95], v[32:47]
	s_waitcnt lgkmcnt(3)
	v_mfma_f32_32x32x16_bf16 v[16:31], v[8:11], v[100:103], v[16:31]
	s_waitcnt lgkmcnt(2)
	v_mfma_f32_32x32x16_bf16 v[16:31], v[88:91], v[104:107], v[16:31]
	s_waitcnt lgkmcnt(1)
	v_mfma_f32_32x32x16_bf16 v[16:31], v[2:5], v[108:111], v[16:31]
	s_waitcnt lgkmcnt(0)
	v_mfma_f32_32x32x16_bf16 v[16:31], v[96:99], v[208:211], v[16:31]

.LBB0_751:
	v_mov_b32_e32 v0, v79
	v_mov_b32_e32 v4, v78
	v_mov_b32_e32 v8, v77
	v_mov_b32_e32 v12, v76
	v_mov_b32_e32 v80, v75
	v_mov_b32_e32 v84, v74
	v_mov_b32_e32 v88, v73
	v_mov_b32_e32 v92, v72
	v_mov_b32_e32 v96, v71
	v_mov_b32_e32 v100, v70
	v_mov_b32_e32 v105, v69
	v_mov_b32_e32 v109, v68
	v_mov_b32_e32 v208, v67
	v_mov_b32_e32 v212, v66
	v_mov_b32_e32 v216, v65
	v_mov_b32_e32 v220, v64
	v_mov_b32_e32 v2, v63
	v_mov_b32_e32 v6, v62
	v_mov_b32_e32 v10, v61
	v_mov_b32_e32 v14, v60
	v_mov_b32_e32 v82, v59
	v_mov_b32_e32 v86, v58
	v_mov_b32_e32 v90, v57
	v_mov_b32_e32 v94, v56
	v_mov_b32_e32 v98, v55
	v_mov_b32_e32 v103, v54
	v_mov_b32_e32 v107, v53
	v_mov_b32_e32 v111, v52
	v_mov_b32_e32 v210, v51
	v_mov_b32_e32 v214, v50
	v_mov_b32_e32 v218, v49
	v_mov_b32_e32 v222, v48
	v_mov_b32_e32 v3, v47
	v_mov_b32_e32 v7, v46
	v_mov_b32_e32 v11, v45
	v_mov_b32_e32 v15, v44
	v_mov_b32_e32 v83, v43
	v_mov_b32_e32 v87, v42
	v_mov_b32_e32 v91, v41
	v_mov_b32_e32 v95, v40
	v_mov_b32_e32 v99, v39
	v_mov_b32_e32 v104, v38
	v_mov_b32_e32 v108, v37
	v_mov_b32_e32 v207, v36
	v_mov_b32_e32 v211, v35
	v_mov_b32_e32 v215, v34
	v_mov_b32_e32 v219, v33
	v_mov_b32_e32 v223, v32
	v_mov_b32_e32 v5, v31
	v_mov_b32_e32 v9, v30
	v_mov_b32_e32 v13, v29
	v_mov_b32_e32 v81, v28
	v_mov_b32_e32 v85, v27
	v_mov_b32_e32 v89, v26
	v_mov_b32_e32 v93, v25
	v_mov_b32_e32 v97, v24
	v_mov_b32_e32 v102, v23
	v_mov_b32_e32 v106, v22
	v_mov_b32_e32 v110, v21
	v_mov_b32_e32 v209, v20
	v_mov_b32_e32 v213, v19
	v_mov_b32_e32 v217, v18
	v_mov_b32_e32 v221, v17
	v_mov_b32_e32 v224, v16
	s_movk_i32 s30, 0xe000
	v_readlane_b32 s54, v248, 43
	v_readlane_b32 s56, v248, 45
	s_mov_b64 s[90:91], s[74:75]
	s_mov_b32 s74, s82
	s_movk_i32 s82, 0xc0
	s_movk_i32 s75, 0x210
	s_mov_b32 s31, -1
	s_mov_b64 s[34:35], 0x4000
	v_readlane_b32 s55, v248, 44
	v_readlane_b32 s57, v248, 46

.LBB0_760:
	s_nop 6
	v_add_f32_e32 v34, v2, v18
	v_add_f32_e32 v34, 0, v34
	v_add_f32_e32 v35, v3, v19
	v_add_f32_e32 v34, v35, v34
	v_add_f32_e32 v35, v4, v20
	v_add_f32_e32 v34, v35, v34
	v_add_f32_e32 v35, v5, v21
	v_add_f32_e32 v46, v35, v34
	v_pk_add_f32 v[44:45], v[6:7], v[22:23]
	v_lshlrev_b32_e32 v109, 4, v197
	v_add_f32_e32 v44, v44, v46
	v_lshlrev_b32_e32 v110, 4, v196
	v_add_u32_e32 v78, 0, v153
	v_pk_add_f32 v[42:43], v[8:9], v[24:25]
	v_add_f32_e32 v44, v45, v44
	v_cvt_pk_bf16_f32 v50, v2, v3
	v_cvt_pk_bf16_f32 v51, v4, v5
	v_add3_u32 v4, v78, v109, v178
	v_add_u32_e32 v2, 0, v110
	v_pk_add_f32 v[38:39], v[12:13], v[28:29]
	v_pk_add_f32 v[40:41], v[10:11], v[26:27]
	v_add_f32_e32 v42, v42, v44
	v_cvt_pk_bf16_f32 v52, v6, v7
	v_cvt_pk_bf16_f32 v53, v8, v9
	v_cvt_pk_bf16_f32 v66, v10, v11
	v_cvt_pk_bf16_f32 v67, v12, v13
	v_cvt_pk_bf16_f32 v68, v14, v15
	v_cvt_pk_bf16_f32 v69, v16, v17
	v_cvt_pk_bf16_f32 v70, v18, v19
	v_cvt_pk_bf16_f32 v71, v20, v21
	v_cvt_pk_bf16_f32 v72, v22, v23
	v_cvt_pk_bf16_f32 v73, v24, v25
	v_cvt_pk_bf16_f32 v74, v26, v27
	v_cvt_pk_bf16_f32 v75, v28, v29
	v_cvt_pk_bf16_f32 v76, v30, v31
	v_cvt_pk_bf16_f32 v77, v32, v33
	v_add3_u32 v6, v2, v178, v153
	ds_read_b64_tr_b16 v[2:3], v4 offset:32768
	ds_read_b64_tr_b16 v[18:19], v4 offset:36864
	ds_read_b64_tr_b16 v[22:23], v4 offset:40960
	ds_read_b64_tr_b16 v[26:27], v4 offset:45056
	ds_read_b64_tr_b16 v[4:5], v6 offset:34816
	ds_read_b64_tr_b16 v[20:21], v6 offset:38912
	ds_read_b64_tr_b16 v[24:25], v6 offset:43008
	ds_read_b64_tr_b16 v[28:29], v6 offset:47104
	v_add_f32_e32 v42, v43, v42
	v_add_f32_e32 v40, v40, v42
	v_add_f32_e32 v40, v41, v40
	v_add_f32_e32 v38, v38, v40
	v_pk_add_f32 v[36:37], v[14:15], v[30:31]
	v_add_f32_e32 v38, v39, v38
	v_add_f32_e32 v36, v36, v38
	v_pk_add_f32 v[34:35], v[16:17], v[32:33]
	v_add_f32_e32 v6, v37, v36
	v_add_f32_e32 v6, v34, v6
	v_add_f32_e32 v6, v35, v6
	v_add_f32_e32 v108, 0, v6
	v_bitop3_b32 v6, v195, v193, 4 bitop3:0x36
	v_lshlrev_b32_e32 v111, 4, v6
	v_bitop3_b32 v6, v195, v194, 4 bitop3:0x36
	v_lshlrev_b32_e32 v144, 4, v6
	v_add3_u32 v6, v78, v111, v178
	v_add_u32_e32 v7, 0, v144
	v_add3_u32 v7, v7, v178, v153
	ds_read_b64_tr_b16 v[30:31], v6 offset:32768
	ds_read_b64_tr_b16 v[34:35], v6 offset:36864
	ds_read_b64_tr_b16 v[38:39], v6 offset:40960
	ds_read_b64_tr_b16 v[42:43], v6 offset:45056
	ds_read_b64_tr_b16 v[32:33], v7 offset:34816
	ds_read_b64_tr_b16 v[36:37], v7 offset:38912
	ds_read_b64_tr_b16 v[40:41], v7 offset:43008
	ds_read_b64_tr_b16 v[44:45], v7 offset:47104
	s_waitcnt lgkmcnt(11)
	v_mfma_f32_32x32x16_bf16 v[2:17], v[50:53], v[2:5], 0
	s_waitcnt lgkmcnt(10)
	v_mfma_f32_32x32x16_bf16 v[2:17], v[66:69], v[18:21], v[2:17]
	s_waitcnt lgkmcnt(9)
	v_mfma_f32_32x32x16_bf16 v[2:17], v[70:73], v[22:25], v[2:17]
	s_waitcnt lgkmcnt(8)
	v_mfma_f32_32x32x16_bf16 v[2:17], v[74:77], v[26:29], v[2:17]
	v_bitop3_b32 v18, v195, v193, 8 bitop3:0x36
	v_lshlrev_b32_e32 v145, 4, v18
	v_bitop3_b32 v18, v195, v194, 8 bitop3:0x36
	v_lshlrev_b32_e32 v146, 4, v18
	v_add3_u32 v18, v78, v145, v178
	v_add_u32_e32 v19, 0, v146
	v_add3_u32 v19, v19, v178, v153
	ds_read_b64_tr_b16 v[46:47], v18 offset:32768
	ds_read_b64_tr_b16 v[54:55], v18 offset:36864
	ds_read_b64_tr_b16 v[58:59], v18 offset:40960
	ds_read_b64_tr_b16 v[62:63], v18 offset:45056
	ds_read_b64_tr_b16 v[48:49], v19 offset:34816
	ds_read_b64_tr_b16 v[56:57], v19 offset:38912
	ds_read_b64_tr_b16 v[60:61], v19 offset:43008
	ds_read_b64_tr_b16 v[64:65], v19 offset:47104
	s_waitcnt lgkmcnt(11)
	v_mfma_f32_32x32x16_bf16 v[18:33], v[50:53], v[30:33], 0
	s_waitcnt lgkmcnt(10)
	v_mfma_f32_32x32x16_bf16 v[18:33], v[66:69], v[34:37], v[18:33]
	s_waitcnt lgkmcnt(9)
	v_mfma_f32_32x32x16_bf16 v[18:33], v[70:73], v[38:41], v[18:33]
	s_waitcnt lgkmcnt(8)
	v_mfma_f32_32x32x16_bf16 v[18:33], v[74:77], v[42:45], v[18:33]
	v_bitop3_b32 v34, v195, v193, 12 bitop3:0x36
	v_lshlrev_b32_e32 v147, 4, v34
	v_bitop3_b32 v34, v195, v194, 12 bitop3:0x36
	v_lshlrev_b32_e32 v149, 4, v34
	v_add3_u32 v34, v78, v147, v178
	v_add_u32_e32 v35, 0, v149
	v_add3_u32 v35, v35, v178, v153
	ds_read_b64_tr_b16 v[78:79], v34 offset:32768
	ds_read_b64_tr_b16 v[82:83], v34 offset:36864
	ds_read_b64_tr_b16 v[86:87], v34 offset:40960
	ds_read_b64_tr_b16 v[90:91], v34 offset:45056
	ds_read_b64_tr_b16 v[80:81], v35 offset:34816
	ds_read_b64_tr_b16 v[84:85], v35 offset:38912
	ds_read_b64_tr_b16 v[88:89], v35 offset:43008
	ds_read_b64_tr_b16 v[92:93], v35 offset:47104
	s_waitcnt lgkmcnt(11)
	v_mfma_f32_32x32x16_bf16 v[34:49], v[50:53], v[46:49], 0
	s_waitcnt lgkmcnt(10)
	v_mfma_f32_32x32x16_bf16 v[34:49], v[66:69], v[54:57], v[34:49]
	s_waitcnt lgkmcnt(9)
	v_mfma_f32_32x32x16_bf16 v[34:49], v[70:73], v[58:61], v[34:49]
	s_waitcnt lgkmcnt(8)
	v_mfma_f32_32x32x16_bf16 v[34:49], v[74:77], v[62:65], v[34:49]
	s_waitcnt lgkmcnt(3)
	v_mfma_f32_32x32x16_bf16 v[50:65], v[50:53], v[78:81], 0
	s_waitcnt lgkmcnt(2)
	v_mfma_f32_32x32x16_bf16 v[50:65], v[66:69], v[82:85], v[50:65]
	s_waitcnt lgkmcnt(1)
	v_mfma_f32_32x32x16_bf16 v[50:65], v[70:73], v[86:89], v[50:65]
	s_waitcnt lgkmcnt(0)
	v_mfma_f32_32x32x16_bf16 v[50:65], v[74:77], v[90:93], v[50:65]
	s_waitcnt vmcnt(0) lgkmcnt(0)
	s_barrier
	s_andn2_b64 vcc, exec, s[6:7]
	s_cbranch_vccnz .LBB0_781
	v_or_b32_e32 v66, s84, v187
	v_or_b32_e32 v67, 32, v66
	v_cmp_le_i32_e32 vcc, v66, v152
	v_cmp_gt_i32_e64 s[6:7], v66, v0
	s_and_b64 s[6:7], vcc, s[6:7]
	v_cmp_le_i32_e32 vcc, v67, v152
	v_cmp_gt_i32_e64 s[8:9], v67, v0
	s_and_b64 s[8:9], vcc, s[8:9]
	v_or_b32_e32 v67, 33, v66
	v_cmp_lt_i32_e32 vcc, v66, v152
	v_cmp_ge_i32_e64 s[10:11], v66, v0
	s_and_b64 s[10:11], vcc, s[10:11]
	v_cmp_le_i32_e32 vcc, v67, v152
	v_cmp_gt_i32_e64 s[12:13], v67, v0
	v_or_b32_e32 v67, 2, v66
	s_and_b64 s[12:13], vcc, s[12:13]
	v_or_b32_e32 v68, 34, v66
	v_cmp_le_i32_e32 vcc, v67, v152
	v_cmp_gt_i32_e64 s[14:15], v67, v0
	s_and_b64 s[14:15], vcc, s[14:15]
	v_cmp_le_i32_e32 vcc, v68, v152
	v_cmp_gt_i32_e64 s[16:17], v68, v0
	v_or_b32_e32 v67, 3, v66
	s_and_b64 s[16:17], vcc, s[16:17]
	v_or_b32_e32 v68, 35, v66
	v_cmp_le_i32_e32 vcc, v67, v152
	v_cmp_gt_i32_e64 s[18:19], v67, v0
	s_and_b64 s[18:19], vcc, s[18:19]
	v_cmp_le_i32_e32 vcc, v68, v152
	v_cmp_gt_i32_e64 s[20:21], v68, v0
	v_or_b32_e32 v67, 8, v66
	s_and_b64 s[20:21], vcc, s[20:21]
	v_or_b32_e32 v68, 40, v66
	v_cmp_le_i32_e32 vcc, v67, v152
	v_cmp_gt_i32_e64 s[22:23], v67, v0
	s_and_b64 s[22:23], vcc, s[22:23]
	v_cmp_le_i32_e32 vcc, v68, v152
	v_cmp_gt_i32_e64 s[24:25], v68, v0
	v_or_b32_e32 v67, 9, v66
	s_and_b64 s[24:25], vcc, s[24:25]
	v_or_b32_e32 v68, 41, v66
	v_cmp_le_i32_e32 vcc, v67, v152
	v_cmp_gt_i32_e64 s[26:27], v67, v0
	s_and_b64 s[26:27], vcc, s[26:27]
	v_cmp_le_i32_e32 vcc, v68, v152
	v_cmp_gt_i32_e64 s[28:29], v68, v0
	v_or_b32_e32 v67, 10, v66
	s_and_b64 s[28:29], vcc, s[28:29]
	v_or_b32_e32 v68, 42, v66
	v_cmp_le_i32_e32 vcc, v67, v152
	v_cmp_gt_i32_e64 s[30:31], v67, v0
	s_and_b64 s[30:31], vcc, s[30:31]
	v_cmp_le_i32_e32 vcc, v68, v152
	v_cmp_gt_i32_e64 s[34:35], v68, v0
	v_or_b32_e32 v67, 11, v66
	s_and_b64 s[34:35], vcc, s[34:35]
	v_or_b32_e32 v68, 43, v66
	v_cmp_le_i32_e32 vcc, v67, v152
	v_cmp_gt_i32_e64 s[36:37], v67, v0
	s_and_b64 s[36:37], vcc, s[36:37]
	v_cmp_le_i32_e32 vcc, v68, v152
	v_cmp_gt_i32_e64 s[38:39], v68, v0
	v_or_b32_e32 v67, 16, v66
	s_and_b64 s[38:39], vcc, s[38:39]
	v_or_b32_e32 v68, 48, v66
	v_cmp_le_i32_e32 vcc, v67, v152
	v_cmp_gt_i32_e64 s[40:41], v67, v0
	s_and_b64 s[40:41], vcc, s[40:41]
	v_cmp_le_i32_e32 vcc, v68, v152
	v_cmp_gt_i32_e64 s[42:43], v68, v0
	v_or_b32_e32 v67, 17, v66
	s_and_b64 s[42:43], vcc, s[42:43]
	v_or_b32_e32 v68, 49, v66
	v_cmp_le_i32_e32 vcc, v67, v152
	v_cmp_gt_i32_e64 s[44:45], v67, v0
	s_and_b64 s[44:45], vcc, s[44:45]
	v_cmp_le_i32_e32 vcc, v68, v152
	v_cmp_gt_i32_e64 s[46:47], v68, v0
	v_or_b32_e32 v67, 18, v66
	s_and_b64 s[46:47], vcc, s[46:47]
	v_or_b32_e32 v68, 50, v66
	v_cmp_le_i32_e32 vcc, v67, v152
	v_cmp_gt_i32_e64 s[48:49], v67, v0
	s_and_b64 s[48:49], vcc, s[48:49]
	v_cmp_le_i32_e32 vcc, v68, v152
	v_cmp_gt_i32_e64 s[50:51], v68, v0
	v_or_b32_e32 v67, 19, v66
	s_and_b64 s[50:51], vcc, s[50:51]
	v_or_b32_e32 v68, 51, v66
	v_cmp_le_i32_e32 vcc, v67, v152
	v_cmp_gt_i32_e64 s[52:53], v67, v0
	s_and_b64 s[52:53], vcc, s[52:53]
	v_cmp_le_i32_e32 vcc, v68, v152
	v_cmp_gt_i32_e64 s[54:55], v68, v0
	v_or_b32_e32 v67, 24, v66
	s_and_b64 s[54:55], vcc, s[54:55]
	v_or_b32_e32 v68, 56, v66
	v_cmp_le_i32_e32 vcc, v67, v152
	v_cmp_gt_i32_e64 s[56:57], v67, v0
	s_and_b64 s[56:57], vcc, s[56:57]
	v_cmp_le_i32_e32 vcc, v68, v152
	v_cmp_gt_i32_e64 s[58:59], v68, v0
	v_or_b32_e32 v67, 25, v66
	s_and_b64 s[58:59], vcc, s[58:59]
	v_or_b32_e32 v68, 57, v66
	v_cmp_le_i32_e32 vcc, v67, v152
	v_cmp_gt_i32_e64 s[60:61], v67, v0
	s_and_b64 s[62:63], vcc, s[60:61]
	v_cmp_le_i32_e32 vcc, v68, v152
	v_cmp_gt_i32_e64 s[60:61], v68, v0
	v_or_b32_e32 v67, 26, v66
	s_and_b64 s[64:65], vcc, s[60:61]
	v_or_b32_e32 v68, 58, v66
	v_cmp_le_i32_e32 vcc, v67, v152
	v_cmp_gt_i32_e64 s[60:61], v67, v0
	s_and_b64 s[66:67], vcc, s[60:61]
	v_cmp_le_i32_e32 vcc, v68, v152
	v_cmp_gt_i32_e64 s[60:61], v68, v0
	v_or_b32_e32 v67, 27, v66
	s_and_b64 s[68:69], vcc, s[60:61]
	v_or_b32_e32 v66, 59, v66
	v_cmp_le_i32_e32 vcc, v67, v152
	v_cmp_gt_i32_e64 s[60:61], v67, v0
	s_and_b64 s[70:71], vcc, s[60:61]
	v_cmp_le_i32_e32 vcc, v66, v152
	v_cmp_gt_i32_e64 s[60:61], v66, v0
	s_sub_i32 s73, s33, s72
	s_and_b64 s[60:61], vcc, s[60:61]
	s_cmp_eq_u32 s73, 1
	s_mov_b32 s76, 1
	s_cbranch_scc0 .LBB0_765
	s_and_b32 s77, s76, 1
	s_cmp_lt_u32 s76, s73
	s_mov_b64 s[2:3], -1
	s_cbranch_scc1 .LBB0_774

.LBB0_764:
	v_add_f32_e32 v72, v68, v0
	v_add_f32_e32 v72, 0, v72
	v_add_f32_e32 v96, v71, v67
	v_add_f32_e32 v72, v96, v72
	v_add_f32_e32 v96, v70, v66
	v_add_f32_e32 v72, v96, v72
	v_add_f32_e32 v96, v73, v69
	v_add_f32_e32 v72, v96, v72
	v_pk_add_f32 v[160:161], v[88:89], v[74:75]
	v_pk_add_f32 v[158:159], v[106:107], v[86:87]
	v_add_f32_e32 v72, v160, v72
	v_add_f32_e32 v72, v161, v72
	v_add_f32_e32 v72, v158, v72
	v_pk_add_f32 v[98:99], v[90:91], v[76:77]
	v_add_f32_e32 v72, v159, v72
	v_add_f32_e32 v72, v98, v72
	v_pk_add_f32 v[96:97], v[92:93], v[78:79]
	v_add_f32_e32 v72, v99, v72
	v_add_f32_e32 v72, v96, v72
	v_pk_add_f32 v[156:157], v[94:95], v[80:81]
	v_add_f32_e32 v72, v97, v72
	v_add_f32_e32 v152, v156, v72
	v_cvt_pk_bf16_f32 v96, v68, v71
	v_cvt_pk_bf16_f32 v97, v70, v73
	v_cvt_pk_bf16_f32 v98, v88, v89
	v_cvt_pk_bf16_f32 v99, v106, v107
	v_cvt_pk_bf16_f32 v70, v90, v91
	v_cvt_pk_bf16_f32 v71, v92, v93
	v_cvt_pk_bf16_f32 v72, v94, v95
	v_cvt_pk_bf16_f32 v73, v84, v85
	v_cvt_pk_bf16_f32 v88, v0, v67
	v_add_u32_e32 v0, s77, v153
	v_cvt_pk_bf16_f32 v89, v66, v69
	v_cvt_pk_bf16_f32 v90, v74, v75
	v_cvt_pk_bf16_f32 v91, v86, v87
	v_cvt_pk_bf16_f32 v66, v76, v77
	v_add3_u32 v76, v0, v109, v178
	v_add_u32_e32 v74, s77, v110
	v_pk_add_f32 v[100:101], v[84:85], v[82:83]
	v_cvt_pk_bf16_f32 v67, v78, v79
	v_cvt_pk_bf16_f32 v68, v80, v81
	v_cvt_pk_bf16_f32 v69, v82, v83
	v_add3_u32 v86, v74, v178, v153
	ds_read_b64_tr_b16 v[74:75], v76 offset:32768
	ds_read_b64_tr_b16 v[78:79], v76 offset:36864
	ds_read_b64_tr_b16 v[82:83], v76 offset:40960
	ds_read_b64_tr_b16 v[92:93], v76 offset:45056
	ds_read_b64_tr_b16 v[76:77], v86 offset:34816
	ds_read_b64_tr_b16 v[80:81], v86 offset:38912
	ds_read_b64_tr_b16 v[84:85], v86 offset:43008
	ds_read_b64_tr_b16 v[94:95], v86 offset:47104
	v_add_f32_e32 v86, v157, v152
	v_add_f32_e32 v86, v100, v86
	v_add_f32_e32 v86, v101, v86
	s_add_i32 s76, s76, 1
	v_add_f32_e32 v108, v108, v86
	v_add3_u32 v86, v0, v111, v178
	v_add_u32_e32 v87, s77, v144
	v_add3_u32 v87, v87, v178, v153
	ds_read_b64_tr_b16 v[156:157], v86 offset:32768
	ds_read_b64_tr_b16 v[194:195], v86 offset:36864
	ds_read_b64_tr_b16 v[198:199], v86 offset:40960
	ds_read_b64_tr_b16 v[202:203], v86 offset:45056
	ds_read_b64_tr_b16 v[158:159], v87 offset:34816
	ds_read_b64_tr_b16 v[196:197], v87 offset:38912
	ds_read_b64_tr_b16 v[200:201], v87 offset:43008
	ds_read_b64_tr_b16 v[204:205], v87 offset:47104
	s_waitcnt lgkmcnt(11)
	v_mfma_f32_32x32x16_bf16 v[2:17], v[96:99], v[74:77], v[2:17]
	s_waitcnt lgkmcnt(10)
	v_mfma_f32_32x32x16_bf16 v[2:17], v[70:73], v[78:81], v[2:17]
	s_waitcnt lgkmcnt(9)
	v_mfma_f32_32x32x16_bf16 v[2:17], v[88:91], v[82:85], v[2:17]
	s_waitcnt lgkmcnt(8)
	v_mfma_f32_32x32x16_bf16 v[2:17], v[66:69], v[92:95], v[2:17]
	v_add3_u32 v76, v0, v145, v178
	v_add_u32_e32 v74, s77, v146
	v_add3_u32 v86, v74, v178, v153
	ds_read_b64_tr_b16 v[74:75], v76 offset:32768
	ds_read_b64_tr_b16 v[78:79], v76 offset:36864
	ds_read_b64_tr_b16 v[82:83], v76 offset:40960
	ds_read_b64_tr_b16 v[92:93], v76 offset:45056
	ds_read_b64_tr_b16 v[76:77], v86 offset:34816
	ds_read_b64_tr_b16 v[80:81], v86 offset:38912
	ds_read_b64_tr_b16 v[84:85], v86 offset:43008
	ds_read_b64_tr_b16 v[94:95], v86 offset:47104
	s_waitcnt lgkmcnt(11)
	v_mfma_f32_32x32x16_bf16 v[18:33], v[96:99], v[156:159], v[18:33]
	s_waitcnt lgkmcnt(10)
	v_mfma_f32_32x32x16_bf16 v[18:33], v[70:73], v[194:197], v[18:33]
	s_waitcnt lgkmcnt(9)
	v_mfma_f32_32x32x16_bf16 v[18:33], v[88:91], v[198:201], v[18:33]
	s_waitcnt lgkmcnt(8)
	v_mfma_f32_32x32x16_bf16 v[18:33], v[66:69], v[202:205], v[18:33]
	v_add3_u32 v0, v0, v147, v178
	v_add_u32_e32 v86, s77, v149
	v_add3_u32 v86, v86, v178, v153
	ds_read_b64_tr_b16 v[156:157], v0 offset:32768
	ds_read_b64_tr_b16 v[194:195], v0 offset:36864
	ds_read_b64_tr_b16 v[198:199], v0 offset:40960
	ds_read_b64_tr_b16 v[202:203], v0 offset:45056
	ds_read_b64_tr_b16 v[158:159], v86 offset:34816
	ds_read_b64_tr_b16 v[196:197], v86 offset:38912
	ds_read_b64_tr_b16 v[200:201], v86 offset:43008
	ds_read_b64_tr_b16 v[204:205], v86 offset:47104
	s_waitcnt lgkmcnt(11)
	v_mfma_f32_32x32x16_bf16 v[34:49], v[96:99], v[74:77], v[34:49]
	s_waitcnt lgkmcnt(10)
	v_mfma_f32_32x32x16_bf16 v[34:49], v[70:73], v[78:81], v[34:49]
	s_waitcnt lgkmcnt(9)
	v_mfma_f32_32x32x16_bf16 v[34:49], v[88:91], v[82:85], v[34:49]
	s_waitcnt lgkmcnt(8)
	v_mfma_f32_32x32x16_bf16 v[34:49], v[66:69], v[92:95], v[34:49]
	s_waitcnt lgkmcnt(3)
	v_mfma_f32_32x32x16_bf16 v[50:65], v[96:99], v[156:159], v[50:65]
	s_waitcnt lgkmcnt(2)
	v_mfma_f32_32x32x16_bf16 v[50:65], v[70:73], v[194:197], v[50:65]
	s_waitcnt lgkmcnt(1)
	v_mfma_f32_32x32x16_bf16 v[50:65], v[88:91], v[198:201], v[50:65]
	s_waitcnt lgkmcnt(0)
	v_mfma_f32_32x32x16_bf16 v[50:65], v[66:69], v[202:205], v[50:65]
	s_waitcnt vmcnt(0) lgkmcnt(0)
	s_barrier
	s_cmp_lg_u32 s73, s76
	s_cbranch_scc0 .LBB0_773

.LBB0_780:
	v_add_f32_e32 v72, v68, v0
	v_add_f32_e32 v72, 0, v72
	v_add_f32_e32 v96, v71, v67
	v_add_f32_e32 v72, v96, v72
	v_add_f32_e32 v96, v70, v66
	v_add_f32_e32 v72, v96, v72
	v_add_f32_e32 v96, v73, v69
	v_add_f32_e32 v72, v96, v72
	v_pk_add_f32 v[112:113], v[88:89], v[74:75]
	v_pk_add_f32 v[106:107], v[102:103], v[86:87]
	v_add_f32_e32 v72, v112, v72
	v_add_f32_e32 v72, v113, v72
	v_add_f32_e32 v72, v106, v72
	v_pk_add_f32 v[98:99], v[90:91], v[76:77]
	v_add_f32_e32 v72, v107, v72
	v_add_f32_e32 v72, v98, v72
	v_pk_add_f32 v[96:97], v[92:93], v[78:79]
	v_add_f32_e32 v72, v99, v72
	v_add_f32_e32 v72, v96, v72
	v_pk_add_f32 v[104:105], v[94:95], v[80:81]
	v_add_f32_e32 v72, v97, v72
	v_add_f32_e32 v104, v104, v72
	v_cvt_pk_bf16_f32 v96, v68, v71
	v_cvt_pk_bf16_f32 v97, v70, v73
	v_cvt_pk_bf16_f32 v98, v88, v89
	v_cvt_pk_bf16_f32 v99, v102, v103
	v_cvt_pk_bf16_f32 v70, v90, v91
	v_cvt_pk_bf16_f32 v71, v92, v93
	v_cvt_pk_bf16_f32 v72, v94, v95
	v_cvt_pk_bf16_f32 v73, v84, v85
	v_cvt_pk_bf16_f32 v88, v0, v67
	v_add_u32_e32 v0, s0, v153
	v_cvt_pk_bf16_f32 v89, v66, v69
	v_cvt_pk_bf16_f32 v90, v74, v75
	v_cvt_pk_bf16_f32 v91, v86, v87
	v_cvt_pk_bf16_f32 v66, v76, v77
	v_add3_u32 v76, v0, v109, v178
	v_add_u32_e32 v74, s0, v110
	v_pk_add_f32 v[100:101], v[84:85], v[82:83]
	v_cvt_pk_bf16_f32 v67, v78, v79
	v_cvt_pk_bf16_f32 v68, v80, v81
	v_cvt_pk_bf16_f32 v69, v82, v83
	v_add3_u32 v86, v74, v178, v153
	ds_read_b64_tr_b16 v[74:75], v76 offset:32768
	ds_read_b64_tr_b16 v[78:79], v76 offset:36864
	ds_read_b64_tr_b16 v[82:83], v76 offset:40960
	ds_read_b64_tr_b16 v[92:93], v76 offset:45056
	ds_read_b64_tr_b16 v[76:77], v86 offset:34816
	ds_read_b64_tr_b16 v[80:81], v86 offset:38912
	ds_read_b64_tr_b16 v[84:85], v86 offset:43008
	ds_read_b64_tr_b16 v[94:95], v86 offset:47104
	v_add_f32_e32 v86, v105, v104
	v_add_f32_e32 v86, v100, v86
	v_add_f32_e32 v86, v101, v86
	v_add_f32_e32 v108, v108, v86
	v_add3_u32 v86, v0, v111, v178
	v_add_u32_e32 v87, s0, v144
	v_add3_u32 v87, v87, v178, v153
	ds_read_b64_tr_b16 v[100:101], v86 offset:32768
	ds_read_b64_tr_b16 v[104:105], v86 offset:36864
	ds_read_b64_tr_b16 v[110:111], v86 offset:40960
	ds_read_b64_tr_b16 v[114:115], v86 offset:45056
	ds_read_b64_tr_b16 v[102:103], v87 offset:34816
	ds_read_b64_tr_b16 v[106:107], v87 offset:38912
	ds_read_b64_tr_b16 v[112:113], v87 offset:43008
	ds_read_b64_tr_b16 v[116:117], v87 offset:47104
	s_waitcnt lgkmcnt(11)
	v_mfma_f32_32x32x16_bf16 v[2:17], v[96:99], v[74:77], v[2:17]
	s_waitcnt lgkmcnt(10)
	v_mfma_f32_32x32x16_bf16 v[2:17], v[70:73], v[78:81], v[2:17]
	s_waitcnt lgkmcnt(9)
	v_mfma_f32_32x32x16_bf16 v[2:17], v[88:91], v[82:85], v[2:17]
	s_waitcnt lgkmcnt(8)
	v_mfma_f32_32x32x16_bf16 v[2:17], v[66:69], v[92:95], v[2:17]
	v_add3_u32 v76, v0, v145, v178
	v_add_u32_e32 v74, s0, v146
	v_add3_u32 v86, v74, v178, v153
	ds_read_b64_tr_b16 v[74:75], v76 offset:32768
	ds_read_b64_tr_b16 v[78:79], v76 offset:36864
	ds_read_b64_tr_b16 v[82:83], v76 offset:40960
	ds_read_b64_tr_b16 v[92:93], v76 offset:45056
	ds_read_b64_tr_b16 v[76:77], v86 offset:34816
	ds_read_b64_tr_b16 v[80:81], v86 offset:38912
	ds_read_b64_tr_b16 v[84:85], v86 offset:43008
	ds_read_b64_tr_b16 v[94:95], v86 offset:47104
	s_waitcnt lgkmcnt(11)
	v_mfma_f32_32x32x16_bf16 v[18:33], v[96:99], v[100:103], v[18:33]
	s_waitcnt lgkmcnt(10)
	v_mfma_f32_32x32x16_bf16 v[18:33], v[70:73], v[104:107], v[18:33]
	s_waitcnt lgkmcnt(9)
	v_mfma_f32_32x32x16_bf16 v[18:33], v[88:91], v[110:113], v[18:33]
	s_waitcnt lgkmcnt(8)
	v_mfma_f32_32x32x16_bf16 v[18:33], v[66:69], v[114:117], v[18:33]
	v_add3_u32 v0, v0, v147, v178
	v_add_u32_e32 v86, s0, v149
	v_add3_u32 v86, v86, v178, v153
	ds_read_b64_tr_b16 v[100:101], v0 offset:32768
	ds_read_b64_tr_b16 v[104:105], v0 offset:36864
	ds_read_b64_tr_b16 v[110:111], v0 offset:40960
	ds_read_b64_tr_b16 v[114:115], v0 offset:45056
	ds_read_b64_tr_b16 v[102:103], v86 offset:34816
	ds_read_b64_tr_b16 v[106:107], v86 offset:38912
	ds_read_b64_tr_b16 v[112:113], v86 offset:43008
	ds_read_b64_tr_b16 v[116:117], v86 offset:47104
	s_waitcnt lgkmcnt(11)
	v_mfma_f32_32x32x16_bf16 v[34:49], v[96:99], v[74:77], v[34:49]
	s_waitcnt lgkmcnt(10)
	v_mfma_f32_32x32x16_bf16 v[34:49], v[70:73], v[78:81], v[34:49]
	s_waitcnt lgkmcnt(9)
	v_mfma_f32_32x32x16_bf16 v[34:49], v[88:91], v[82:85], v[34:49]
	s_waitcnt lgkmcnt(8)
	v_mfma_f32_32x32x16_bf16 v[34:49], v[66:69], v[92:95], v[34:49]
	s_waitcnt lgkmcnt(3)
	v_mfma_f32_32x32x16_bf16 v[50:65], v[96:99], v[100:103], v[50:65]
	s_waitcnt lgkmcnt(2)
	v_mfma_f32_32x32x16_bf16 v[50:65], v[70:73], v[104:107], v[50:65]
	s_waitcnt lgkmcnt(1)
	v_mfma_f32_32x32x16_bf16 v[50:65], v[88:91], v[110:113], v[50:65]
	s_waitcnt lgkmcnt(0)
	v_mfma_f32_32x32x16_bf16 v[50:65], v[66:69], v[114:117], v[50:65]
	s_waitcnt vmcnt(0) lgkmcnt(0)
	s_barrier
	s_movk_i32 s30, 0xe000
	v_readlane_b32 s54, v248, 43
	v_readlane_b32 s56, v248, 45
	s_mov_b32 s31, -1
	s_mov_b64 s[34:35], 0x4000
	v_readlane_b32 s55, v248, 44
	v_readlane_b32 s57, v248, 46

.LBB0_784:
	s_setprio 0
	s_waitcnt vmcnt(0) lgkmcnt(0)
	s_load_dwordx2 s[36:37], s[90:91], 0xf0
	s_waitcnt lgkmcnt(0)
	s_getreg_b32 s0, hwreg(HW_REG_XCC_ID, 0, 4)
	v_mbcnt_lo_u32_b32 v0, -1, 0
	v_mbcnt_hi_u32_b32 v0, -1, v0
	s_waitcnt vmcnt(0)
	s_nop 0
	v_sub_u32_e32 v0, 0, v0
	v_cmp_eq_u32_e32 vcc, s83, v0
	s_barrier
	s_and_saveexec_b64 s[2:3], vcc
	v_readlane_b32 s70, v248, 18
	v_readlane_b32 s71, v248, 19
	v_readlane_b32 s76, v248, 22
	v_readlane_b32 s80, v248, 24
	v_readlane_b32 s84, v248, 26
	v_readlane_b32 s78, v248, 28
	v_readlane_b32 s71, v248, 20
	v_readlane_b32 s72, v248, 21
	v_readlane_b32 s77, v248, 23
	v_readlane_b32 s81, v248, 25
	v_readlane_b32 s85, v248, 27
	v_readlane_b32 s73, v248, 30
	v_readlane_b32 s79, v248, 29
	s_movk_i32 s75, 0xa9
	s_mov_b64 s[86:87], 0x10000000
	s_cbranch_execz .LBB0_828
	v_readlane_b32 s1, v248, 6
	s_waitcnt vmcnt(0) expcnt(0) lgkmcnt(0)
	s_and_b32 s0, s0, 15
	v_mov_b32_e32 v0, s1
	ds_read_b32 v2, v0
	v_readlane_b32 s1, v248, 7
	s_waitcnt lgkmcnt(0)
	v_cmp_ne_u32_e32 vcc, 0, v2
	v_mov_b32_e32 v0, s1
	ds_read_b32 v0, v0
	s_cbranch_vccnz .LBB0_799
	s_add_u32 s4, s36, 0x27f00200
	s_addc_u32 s5, s37, 0
	s_add_u32 s6, s36, 0x27f00400
	s_addc_u32 s7, s37, 0
	s_add_u32 s8, s36, 0x27f00500
	s_addc_u32 s9, s37, 0
	s_add_u32 s10, s36, 0x27f00600
	s_addc_u32 s11, s37, 0
	s_add_u32 s12, s36, 0x27f00700
	s_addc_u32 s13, s37, 0
	s_add_u32 s14, s36, 0x27f00800
	s_addc_u32 s15, s37, 0
	s_add_u32 s16, s36, 0x27f00900
	s_addc_u32 s17, s37, 0
	s_add_u32 s18, s36, 0x27f00a00
	s_addc_u32 s19, s37, 0
	s_add_u32 s20, s36, 0x27f00b00
	s_addc_u32 s21, s37, 0
	s_add_u32 s22, s36, 0x27f00c00
	s_addc_u32 s23, s37, 0
	s_add_u32 s24, s36, 0x27f00d00
	s_addc_u32 s25, s37, 0
	s_add_u32 s26, s36, 0x27f00e00
	s_addc_u32 s27, s37, 0
	s_add_u32 s28, s36, 0x27f00f00
	s_addc_u32 s29, s37, 0
	s_add_u32 s30, s36, 0x27f01000
	s_addc_u32 s31, s37, 0
	s_add_u32 s34, s36, 0x27f01100
	s_addc_u32 s35, s37, 0
	s_add_u32 s38, s36, 0x27f01200
	s_addc_u32 s39, s37, 0
	s_add_u32 s40, s36, 0x27f01300
	s_addc_u32 s41, s37, 0
	s_mov_b32 s1, 1
	s_mov_b64 s[42:43], 0
	s_branch .LBB0_789
